# dilated attention: O and LSE stores made write-through (sc1) so they do not take XCD-L2 capacity from the K/V rows reused by neighbouring items
# baseline (speedup 1.0000x reference)
.LBB0_509:
	s_or_b64 exec, exec, s[8:9]
	s_waitcnt lgkmcnt(0)
	ds_read_b128 v[68:71], v214 offset:8448
	ds_read_b128 v[72:75], v214 offset:8480
	v_lshlrev_b64 v[76:77], 25, v[66:67]
	s_lshl_b32 s72, s57, 8
	v_mov_b32_e32 v185, v1
	s_waitcnt lgkmcnt(1)
	v_rcp_f32_e32 v0, v68
	v_rcp_f32_e32 v78, v69
	v_rcp_f32_e32 v79, v70
	v_rcp_f32_e32 v80, v71
	v_mul_f32_e32 v50, v50, v0
	v_mul_f32_e32 v34, v34, v0
	v_mul_f32_e32 v18, v18, v0
	v_mul_f32_e32 v0, v2, v0
	s_waitcnt lgkmcnt(0)
	v_rcp_f32_e32 v81, v72
	ds_read_b128 v[66:69], v214 offset:8512
	v_rcp_f32_e32 v82, v73
	ds_read_b128 v[70:73], v214 offset:8544
	s_waitcnt lgkmcnt(0)
	v_cvt_pk_bf16_f32 v50, v50, v1
	ds_write_b16 v226, v50
	v_cvt_pk_bf16_f32 v34, v34, v1
	ds_write_b16 v226, v34 offset:64
	v_cvt_pk_bf16_f32 v18, v18, v1
	ds_write_b16 v226, v18 offset:128
	v_cvt_pk_bf16_f32 v0, v0, v1
	ds_write_b16 v226, v0 offset:192
	v_mul_f32_e32 v0, v51, v78
	v_cvt_pk_bf16_f32 v0, v0, v1
	v_add_u32_e32 v2, v216, v215
	ds_write_b16 v2, v0
	v_mul_f32_e32 v0, v35, v78
	v_cvt_pk_bf16_f32 v0, v0, v1
	ds_write_b16 v2, v0 offset:64
	v_mul_f32_e32 v0, v19, v78
	v_cvt_pk_bf16_f32 v0, v0, v1
	ds_write_b16 v2, v0 offset:128
	v_mul_f32_e32 v0, v3, v78
	v_cvt_pk_bf16_f32 v0, v0, v1
	ds_write_b16 v2, v0 offset:192
	v_mul_f32_e32 v0, v52, v79
	v_cvt_pk_bf16_f32 v0, v0, v1
	ds_write_b16 v227, v0
	v_mul_f32_e32 v0, v36, v79
	v_cvt_pk_bf16_f32 v0, v0, v1
	ds_write_b16 v227, v0 offset:64
	v_mul_f32_e32 v0, v20, v79
	v_cvt_pk_bf16_f32 v0, v0, v1
	ds_write_b16 v227, v0 offset:128
	v_mul_f32_e32 v0, v4, v79
	v_cvt_pk_bf16_f32 v0, v0, v1
	ds_write_b16 v227, v0 offset:192
	v_mul_f32_e32 v0, v53, v80
	v_cvt_pk_bf16_f32 v0, v0, v1
	ds_write_b16 v228, v0
	v_mul_f32_e32 v0, v37, v80
	v_cvt_pk_bf16_f32 v0, v0, v1
	ds_write_b16 v228, v0 offset:64
	v_mul_f32_e32 v0, v21, v80
	v_cvt_pk_bf16_f32 v0, v0, v1
	ds_write_b16 v228, v0 offset:128
	v_mul_f32_e32 v0, v5, v80
	v_cvt_pk_bf16_f32 v0, v0, v1
	ds_write_b16 v228, v0 offset:192
	v_mul_f32_e32 v0, v54, v81
	v_cvt_pk_bf16_f32 v0, v0, v1
	ds_write_b16 v229, v0
	v_mul_f32_e32 v0, v38, v81
	v_cvt_pk_bf16_f32 v0, v0, v1
	ds_write_b16 v229, v0 offset:64
	v_mul_f32_e32 v0, v22, v81
	v_cvt_pk_bf16_f32 v0, v0, v1
	ds_write_b16 v229, v0 offset:128
	v_mul_f32_e32 v0, v6, v81
	v_cvt_pk_bf16_f32 v0, v0, v1
	ds_write_b16 v229, v0 offset:192
	v_mul_f32_e32 v0, v55, v82
	v_cvt_pk_bf16_f32 v0, v0, v1
	ds_write_b16 v230, v0
	v_mul_f32_e32 v0, v39, v82
	v_cvt_pk_bf16_f32 v0, v0, v1
	v_rcp_f32_e32 v74, v74
	ds_write_b16 v230, v0 offset:64
	v_mul_f32_e32 v0, v23, v82
	v_cvt_pk_bf16_f32 v0, v0, v1
	ds_write_b16 v230, v0 offset:128
	v_mul_f32_e32 v0, v7, v82
	v_cvt_pk_bf16_f32 v0, v0, v1
	ds_write_b16 v230, v0 offset:192
	v_mul_f32_e32 v0, v56, v74
	v_cvt_pk_bf16_f32 v0, v0, v1
	ds_write_b16 v231, v0
	v_mul_f32_e32 v0, v40, v74
	v_cvt_pk_bf16_f32 v0, v0, v1
	v_rcp_f32_e32 v75, v75
	ds_write_b16 v231, v0 offset:64
	v_mul_f32_e32 v0, v24, v74
	v_cvt_pk_bf16_f32 v0, v0, v1
	ds_write_b16 v231, v0 offset:128
	v_mul_f32_e32 v0, v8, v74
	v_cvt_pk_bf16_f32 v0, v0, v1
	ds_write_b16 v231, v0 offset:192
	v_mul_f32_e32 v0, v57, v75
	v_cvt_pk_bf16_f32 v0, v0, v1
	ds_write_b16 v232, v0
	v_mul_f32_e32 v0, v41, v75
	v_cvt_pk_bf16_f32 v0, v0, v1
	s_waitcnt lgkmcnt(14)
	v_rcp_f32_e32 v66, v66
	ds_write_b16 v232, v0 offset:64
	v_mul_f32_e32 v0, v25, v75
	v_cvt_pk_bf16_f32 v0, v0, v1
	ds_write_b16 v232, v0 offset:128
	v_mul_f32_e32 v0, v9, v75
	v_cvt_pk_bf16_f32 v0, v0, v1
	ds_write_b16 v232, v0 offset:192
	v_mul_f32_e32 v0, v58, v66
	v_cvt_pk_bf16_f32 v0, v0, v1
	ds_write_b16 v233, v0
	v_mul_f32_e32 v0, v42, v66
	v_cvt_pk_bf16_f32 v0, v0, v1
	v_rcp_f32_e32 v67, v67
	ds_write_b16 v233, v0 offset:64
	v_mul_f32_e32 v0, v26, v66
	v_cvt_pk_bf16_f32 v0, v0, v1
	ds_write_b16 v233, v0 offset:128
	v_mul_f32_e32 v0, v10, v66
	v_cvt_pk_bf16_f32 v0, v0, v1
	ds_write_b16 v233, v0 offset:192
	v_mul_f32_e32 v0, v59, v67
	v_cvt_pk_bf16_f32 v0, v0, v1
	ds_write_b16 v234, v0
	v_mul_f32_e32 v0, v43, v67
	v_cvt_pk_bf16_f32 v0, v0, v1
	v_rcp_f32_e32 v68, v68
	ds_write_b16 v234, v0 offset:64
	v_mul_f32_e32 v0, v27, v67
	v_cvt_pk_bf16_f32 v0, v0, v1
	ds_write_b16 v234, v0 offset:128
	v_mul_f32_e32 v0, v11, v67
	v_cvt_pk_bf16_f32 v0, v0, v1
	ds_write_b16 v234, v0 offset:192
	v_mul_f32_e32 v0, v60, v68
	v_cvt_pk_bf16_f32 v0, v0, v1
	ds_write_b16 v235, v0
	v_mul_f32_e32 v0, v44, v68
	v_cvt_pk_bf16_f32 v0, v0, v1
	v_rcp_f32_e32 v69, v69
	ds_write_b16 v235, v0 offset:64
	v_mul_f32_e32 v0, v28, v68
	v_cvt_pk_bf16_f32 v0, v0, v1
	ds_write_b16 v235, v0 offset:128
	v_mul_f32_e32 v0, v12, v68
	v_cvt_pk_bf16_f32 v0, v0, v1
	ds_write_b16 v235, v0 offset:192
	v_mul_f32_e32 v0, v61, v69
	v_cvt_pk_bf16_f32 v0, v0, v1
	ds_write_b16 v236, v0
	v_mul_f32_e32 v0, v45, v69
	v_cvt_pk_bf16_f32 v0, v0, v1
	v_rcp_f32_e32 v70, v70
	ds_write_b16 v236, v0 offset:64
	v_mul_f32_e32 v0, v29, v69
	v_cvt_pk_bf16_f32 v0, v0, v1
	ds_write_b16 v236, v0 offset:128
	v_mul_f32_e32 v0, v13, v69
	v_cvt_pk_bf16_f32 v0, v0, v1
	ds_write_b16 v236, v0 offset:192
	v_mul_f32_e32 v0, v62, v70
	v_cvt_pk_bf16_f32 v0, v0, v1
	ds_write_b16 v237, v0
	v_mul_f32_e32 v0, v46, v70
	v_cvt_pk_bf16_f32 v0, v0, v1
	v_rcp_f32_e32 v71, v71
	ds_write_b16 v237, v0 offset:64
	v_mul_f32_e32 v0, v30, v70
	v_cvt_pk_bf16_f32 v0, v0, v1
	ds_write_b16 v237, v0 offset:128
	v_mul_f32_e32 v0, v14, v70
	v_cvt_pk_bf16_f32 v0, v0, v1
	ds_write_b16 v237, v0 offset:192
	v_mul_f32_e32 v0, v63, v71
	v_cvt_pk_bf16_f32 v0, v0, v1
	ds_write_b16 v238, v0
	v_mul_f32_e32 v0, v47, v71
	v_cvt_pk_bf16_f32 v0, v0, v1
	v_rcp_f32_e32 v72, v72
	ds_write_b16 v238, v0 offset:64
	v_mul_f32_e32 v0, v31, v71
	v_cvt_pk_bf16_f32 v0, v0, v1
	ds_write_b16 v238, v0 offset:128
	v_mul_f32_e32 v0, v15, v71
	v_cvt_pk_bf16_f32 v0, v0, v1
	ds_write_b16 v238, v0 offset:192
	v_mul_f32_e32 v0, v64, v72
	v_cvt_pk_bf16_f32 v0, v0, v1
	ds_write_b16 v239, v0
	v_mul_f32_e32 v0, v48, v72
	v_cvt_pk_bf16_f32 v0, v0, v1
	v_rcp_f32_e32 v73, v73
	ds_write_b16 v239, v0 offset:64
	v_mul_f32_e32 v0, v32, v72
	v_cvt_pk_bf16_f32 v0, v0, v1
	ds_write_b16 v239, v0 offset:128
	v_mul_f32_e32 v0, v16, v72
	v_cvt_pk_bf16_f32 v0, v0, v1
	ds_write_b16 v239, v0 offset:192
	v_mul_f32_e32 v0, v65, v73
	v_cvt_pk_bf16_f32 v0, v0, v1
	ds_write_b16 v240, v0
	v_mul_f32_e32 v0, v49, v73
	v_cvt_pk_bf16_f32 v0, v0, v1
	ds_write_b16 v240, v0 offset:64
	v_mul_f32_e32 v0, v33, v73
	v_cvt_pk_bf16_f32 v0, v0, v1
	ds_write_b16 v240, v0 offset:128
	v_mul_f32_e32 v0, v17, v73
	v_cvt_pk_bf16_f32 v0, v0, v1
	ds_write_b16 v240, v0 offset:192
	v_lshl_add_u64 v[2:3], s[24:25], 0, v[76:77]
	s_waitcnt lgkmcnt(0)
	v_lshl_add_u64 v[2:3], v[2:3], 0, s[72:73]
	v_add_u32_e32 v6, s56, v204
	v_lshl_add_u64 v[10:11], v[2:3], 0, v[184:185]
	ds_read_b128 v[2:5], v241
	v_ashrrev_i32_e32 v7, 31, v6
	v_lshlrev_b64 v[6:7], s55, v[6:7]
	v_lshl_add_u64 v[6:7], v[6:7], 0, s[10:11]
	v_lshlrev_b64 v[6:7], 10, v[6:7]
	v_lshl_add_u64 v[12:13], v[10:11], 0, v[6:7]
	ds_read_b128 v[6:9], v241 offset:1088
	s_waitcnt lgkmcnt(1)
	global_store_dwordx4 v[12:13], v[2:5], off sc1
	s_add_i32 s54, s54, s46
	s_cmpk_gt_i32 s54, 0x2fff
	v_add_u32_e32 v2, s56, v207
	v_ashrrev_i32_e32 v3, 31, v2
	v_lshlrev_b64 v[2:3], s55, v[2:3]
	v_lshl_add_u64 v[2:3], v[2:3], 0, s[10:11]
	v_lshlrev_b64 v[2:3], 10, v[2:3]
	v_lshl_add_u64 v[2:3], v[10:11], 0, v[2:3]
	s_waitcnt lgkmcnt(0)
	global_store_dwordx4 v[2:3], v[6:9], off sc1
	ds_read_b128 v[2:5], v241 offset:2176
	s_nop 0
	v_add_u32_e32 v6, s56, v208
	v_ashrrev_i32_e32 v7, 31, v6
	v_lshlrev_b64 v[6:7], s55, v[6:7]
	v_lshl_add_u64 v[6:7], v[6:7], 0, s[10:11]
	v_lshlrev_b64 v[6:7], 10, v[6:7]
	v_lshl_add_u64 v[12:13], v[10:11], 0, v[6:7]
	ds_read_b128 v[6:9], v241 offset:3264
	s_waitcnt lgkmcnt(1)
	global_store_dwordx4 v[12:13], v[2:5], off sc1
	s_nop 1
	v_add_u32_e32 v2, s56, v209
	v_ashrrev_i32_e32 v3, 31, v2
	v_lshlrev_b64 v[2:3], s55, v[2:3]
	v_lshl_add_u64 v[2:3], v[2:3], 0, s[10:11]
	v_lshlrev_b64 v[2:3], 10, v[2:3]
	v_lshl_add_u64 v[2:3], v[10:11], 0, v[2:3]
	s_waitcnt lgkmcnt(0)
	global_store_dwordx4 v[2:3], v[6:9], off sc1
	ds_read_b128 v[2:5], v241 offset:4352
	s_nop 0
	v_add_u32_e32 v6, s56, v210
	v_ashrrev_i32_e32 v7, 31, v6
	v_lshlrev_b64 v[6:7], s55, v[6:7]
	v_lshl_add_u64 v[6:7], v[6:7], 0, s[10:11]
	v_lshlrev_b64 v[6:7], 10, v[6:7]
	v_lshl_add_u64 v[12:13], v[10:11], 0, v[6:7]
	ds_read_b128 v[6:9], v241 offset:5440
	s_waitcnt lgkmcnt(1)
	global_store_dwordx4 v[12:13], v[2:5], off sc1
	s_nop 1
	v_add_u32_e32 v2, s56, v211
	v_ashrrev_i32_e32 v3, 31, v2
	v_lshlrev_b64 v[2:3], s55, v[2:3]
	v_lshl_add_u64 v[2:3], v[2:3], 0, s[10:11]
	v_lshlrev_b64 v[2:3], 10, v[2:3]
	v_lshl_add_u64 v[2:3], v[10:11], 0, v[2:3]
	s_waitcnt lgkmcnt(0)
	global_store_dwordx4 v[2:3], v[6:9], off sc1
	ds_read_b128 v[2:5], v241 offset:6528
	s_nop 0
	v_add_u32_e32 v6, s56, v212
	v_ashrrev_i32_e32 v7, 31, v6
	v_lshlrev_b64 v[6:7], s55, v[6:7]
	v_lshl_add_u64 v[6:7], v[6:7], 0, s[10:11]
	v_lshlrev_b64 v[6:7], 10, v[6:7]
	v_lshl_add_u64 v[12:13], v[10:11], 0, v[6:7]
	ds_read_b128 v[6:9], v241 offset:7616
	s_waitcnt lgkmcnt(1)
	global_store_dwordx4 v[12:13], v[2:5], off sc1
	s_nop 1
	v_add_u32_e32 v2, s56, v213
	v_ashrrev_i32_e32 v3, 31, v2
	v_lshlrev_b64 v[2:3], s55, v[2:3]
	v_lshl_add_u64 v[2:3], v[2:3], 0, s[10:11]
	v_lshlrev_b64 v[2:3], 10, v[2:3]
	v_lshl_add_u64 v[2:3], v[10:11], 0, v[2:3]
	s_waitcnt lgkmcnt(0)
	global_store_dwordx4 v[2:3], v[6:9], off sc1
	s_waitcnt lgkmcnt(0)
	s_cbranch_scc1 .LBB0_523

.LBB0_519:
	s_and_saveexec_b64 s[8:9], s[4:5]
	s_xor_b64 s[8:9], exec, s[8:9]
	s_ashr_i32 s51, s50, 31
	s_or_saveexec_b64 s[8:9], s[8:9]
	v_mov_b64_e32 v[66:67], s[50:51]
	s_xor_b64 exec, exec, s[8:9]
	s_cbranch_execz .LBB0_509
	s_ashr_i32 s51, s50, 31
	v_log_f32_e32 v66, v75
	s_lshl_b64 s[16:17], s[50:51], 15
	s_add_u32 s16, s16, s52
	s_addc_u32 s17, s17, s53
	s_or_b64 s[16:17], s[16:17], s[72:73]
	v_add_f32_e32 v0, v0, v66
	v_lshl_add_u64 v[66:67], s[16:17], 0, v[186:187]
	v_lshl_add_u64 v[66:67], v[66:67], 4, s[20:21]
	s_lshl_b32 s72, s57, 2
	v_lshl_add_u64 v[66:67], v[66:67], 0, s[72:73]
	global_store_dword v[66:67], v0, off sc1
	v_mov_b64_e32 v[66:67], s[50:51]
	ds_write_b32 v206, v75 offset:8448
	s_branch .LBB0_509
